# layer-1 adaLN GEMV item (end of in-proj phase): 32 weight loads of a trip issued together with counted vmcnt, same fma order
# speedup vs baseline: 1.0089x; 1.0089x over previous
; DI void phase_ada_item(CP p, const Ptrs& w, int l, int item, int ksplit, float* sm) {
;     ...
;   const float* wa = p.in[5] + (size_t)l * 2048 * 6144 + j;
;   float a0 = 0.f, a1 = 0.f, a2 = 0.f;
;   const int kb = kq * (2048 / ksplit) + wid * rows_w;
; #pragma unroll 32
;   for (int k = 0; k < rows_w; ++k) {
;     float wv = wa[(size_t)(kb + k) * 6144];
;     a0 += act[kb + k] * wv; a1 += act[2048 + kb + k] * wv; a2 += act[4096 + kb + k] * wv;
.LBB0_245:
	s_or_b64 exec, exec, s[38:39]
	s_mul_hi_i32 s17, s16, 0x2aaaaaab
	s_lshr_b32 s38, s17, 31
	s_ashr_i32 s17, s17, 4
	s_add_i32 s17, s17, s38
	s_mul_i32 s38, s17, 0x60
	v_and_b32_e32 v19, 63, v8
	s_sub_i32 s16, s16, s38
	v_lshl_or_b32 v10, s16, 6, v19
	v_ashrrev_i32_e32 v9, 6, v8
	v_ashrrev_i32_e32 v11, 31, v10
	s_lshl_b32 s16, s17, 11
	v_lshl_add_u32 v2, v9, 9, s16
	v_lshlrev_b64 v[0:1], 2, v[10:11]
	v_mad_i64_i32 v[0:1], s[16:17], v2, s21, v[0:1]
	s_waitcnt vmcnt(2)
	v_mov_b32_e32 v20, 0
	v_lshlrev_b32_e32 v21, 2, v2
	v_lshl_add_u64 v[12:13], s[4:5], 0, v[0:1]
	s_mov_b64 s[38:39], 0
	v_mov_b32_e32 v16, 0
	v_mov_b32_e32 v17, v20
	s_waitcnt lgkmcnt(0)
	s_barrier
	v_subrev_u32_e32 v156, s4, v12
.LBB0_246:
	s_add_u32 s100, s4, s38
	s_addc_u32 s101, s5, s39
	s_add_u32 s100, s100, 0x3000000
	s_addc_u32 s101, s101, 0
	ds_read_b128 v[0:3], v21
	ds_read_b128 v[4:7], v21 offset:8192
	ds_read_b128 v[22:25], v21 offset:16384
	global_load_dword v96, v156, s[100:101]
	s_add_u32 s100, s100, 0x6000
	s_addc_u32 s101, s101, 0
	global_load_dword v97, v156, s[100:101]
	s_add_u32 s100, s100, 0x6000
	s_addc_u32 s101, s101, 0
	global_load_dword v98, v156, s[100:101]
	s_add_u32 s100, s100, 0x6000
	s_addc_u32 s101, s101, 0
	global_load_dword v99, v156, s[100:101]
	s_add_u32 s100, s100, 0x6000
	s_addc_u32 s101, s101, 0
	global_load_dword v100, v156, s[100:101]
	s_add_u32 s100, s100, 0x6000
	s_addc_u32 s101, s101, 0
	global_load_dword v101, v156, s[100:101]
	s_add_u32 s100, s100, 0x6000
	s_addc_u32 s101, s101, 0
	global_load_dword v102, v156, s[100:101]
	s_add_u32 s100, s100, 0x6000
	s_addc_u32 s101, s101, 0
	global_load_dword v103, v156, s[100:101]
	s_add_u32 s100, s100, 0x6000
	s_addc_u32 s101, s101, 0
	global_load_dword v104, v156, s[100:101]
	s_add_u32 s100, s100, 0x6000
	s_addc_u32 s101, s101, 0
	global_load_dword v105, v156, s[100:101]
	s_add_u32 s100, s100, 0x6000
	s_addc_u32 s101, s101, 0
	global_load_dword v106, v156, s[100:101]
	s_add_u32 s100, s100, 0x6000
	s_addc_u32 s101, s101, 0
	global_load_dword v107, v156, s[100:101]
	s_add_u32 s100, s100, 0x6000
	s_addc_u32 s101, s101, 0
	global_load_dword v108, v156, s[100:101]
	s_add_u32 s100, s100, 0x6000
	s_addc_u32 s101, s101, 0
	global_load_dword v109, v156, s[100:101]
	s_add_u32 s100, s100, 0x6000
	s_addc_u32 s101, s101, 0
	global_load_dword v110, v156, s[100:101]
	s_add_u32 s100, s100, 0x6000
	s_addc_u32 s101, s101, 0
	global_load_dword v111, v156, s[100:101]
	s_add_u32 s100, s100, 0x6000
	s_addc_u32 s101, s101, 0
	global_load_dword v112, v156, s[100:101]
	s_add_u32 s100, s100, 0x6000
	s_addc_u32 s101, s101, 0
	global_load_dword v113, v156, s[100:101]
	s_add_u32 s100, s100, 0x6000
	s_addc_u32 s101, s101, 0
	global_load_dword v114, v156, s[100:101]
	s_add_u32 s100, s100, 0x6000
	s_addc_u32 s101, s101, 0
	global_load_dword v115, v156, s[100:101]
	s_add_u32 s100, s100, 0x6000
	s_addc_u32 s101, s101, 0
	global_load_dword v116, v156, s[100:101]
	s_add_u32 s100, s100, 0x6000
	s_addc_u32 s101, s101, 0
	global_load_dword v117, v156, s[100:101]
	s_add_u32 s100, s100, 0x6000
	s_addc_u32 s101, s101, 0
	global_load_dword v118, v156, s[100:101]
	s_add_u32 s100, s100, 0x6000
	s_addc_u32 s101, s101, 0
	global_load_dword v119, v156, s[100:101]
	s_add_u32 s100, s100, 0x6000
	s_addc_u32 s101, s101, 0
	global_load_dword v120, v156, s[100:101]
	s_add_u32 s100, s100, 0x6000
	s_addc_u32 s101, s101, 0
	global_load_dword v121, v156, s[100:101]
	s_add_u32 s100, s100, 0x6000
	s_addc_u32 s101, s101, 0
	global_load_dword v122, v156, s[100:101]
	s_add_u32 s100, s100, 0x6000
	s_addc_u32 s101, s101, 0
	global_load_dword v123, v156, s[100:101]
	s_add_u32 s100, s100, 0x6000
	s_addc_u32 s101, s101, 0
	global_load_dword v124, v156, s[100:101]
	s_add_u32 s100, s100, 0x6000
	s_addc_u32 s101, s101, 0
	global_load_dword v125, v156, s[100:101]
	s_add_u32 s100, s100, 0x6000
	s_addc_u32 s101, s101, 0
	global_load_dword v126, v156, s[100:101]
	s_add_u32 s100, s100, 0x6000
	s_addc_u32 s101, s101, 0
	global_load_dword v127, v156, s[100:101]
	s_add_u32 s38, s38, 0xc0000
	s_addc_u32 s39, s39, 0
	ds_read_b128 v[26:29], v21 offset:16
	ds_read_b128 v[30:33], v21 offset:8208
	ds_read_b128 v[34:37], v21 offset:16400
	s_waitcnt lgkmcnt(3)
	s_waitcnt vmcnt(31)
	v_fmac_f32_e32 v16, v96, v0
	v_fmac_f32_e32 v17, v96, v4
	v_fmac_f32_e32 v20, v96, v22
	s_waitcnt vmcnt(30)
	v_fmac_f32_e32 v16, v97, v1
	v_fmac_f32_e32 v17, v97, v5
	v_fmac_f32_e32 v20, v97, v23
	s_waitcnt vmcnt(29)
	v_fmac_f32_e32 v16, v98, v2
	v_fmac_f32_e32 v17, v98, v6
	v_fmac_f32_e32 v20, v98, v24
	s_waitcnt vmcnt(28)
	v_fmac_f32_e32 v16, v99, v3
	v_fmac_f32_e32 v17, v99, v7
	v_fmac_f32_e32 v20, v99, v25
	ds_read_b128 v[0:3], v21 offset:32
	ds_read_b128 v[4:7], v21 offset:8224
	ds_read_b128 v[22:25], v21 offset:16416
	s_waitcnt lgkmcnt(3)
	s_waitcnt vmcnt(27)
	v_fmac_f32_e32 v16, v100, v26
	v_fmac_f32_e32 v17, v100, v30
	v_fmac_f32_e32 v20, v100, v34
	s_waitcnt vmcnt(26)
; DI void phase_ada_item(CP p, const Ptrs& w, int l, int item, int ksplit, float* sm) {
;     ...
;   for (int k = 0; k < rows_w; ++k) {
;     float wv = wa[(size_t)(kb + k) * 6144];
;     a0 += act[kb + k] * wv; a1 += act[2048 + kb + k] * wv; a2 += act[4096 + kb + k] * wv;
;   }
;   red[(wid * 3 + 0) * 64 + lane] = a0; red[(wid * 3 + 1) * 64 + lane] = a1; red[(wid * 3 + 2) * 64 + lane] = a2;
;   __syncthreads();
;   if (tid < 192) {
;     int v = tid >> 6, ll = tid & 63, jj = cgp * 64 + ll;
;     float s = red[(0 * 3 + v) * 64 + ll] + red[(1 * 3 + v) * 64 + ll] + red[(2 * 3 + v) * 64 + ll] + red[(3 * 3 + v) * 64 + ll];
;     if (ksplit == 1) w.mod[(l * 3 + v) * 6144 + jj] = s + p.in[6][l * 6144 + jj];
;     else atomicAdd(&w.mod[(l * 3 + v) * 6144 + jj], kq == 0 ? s + p.in[6][l * 6144 + jj] : s);
;   }
	v_fmac_f32_e32 v16, v101, v27
	v_fmac_f32_e32 v17, v101, v31
	v_fmac_f32_e32 v20, v101, v35
	s_waitcnt vmcnt(25)
	v_fmac_f32_e32 v16, v102, v28
	v_fmac_f32_e32 v17, v102, v32
	v_fmac_f32_e32 v20, v102, v36
	s_waitcnt vmcnt(24)
	v_fmac_f32_e32 v16, v103, v29
	v_fmac_f32_e32 v17, v103, v33
	v_fmac_f32_e32 v20, v103, v37
	ds_read_b128 v[26:29], v21 offset:48
	ds_read_b128 v[30:33], v21 offset:8240
	ds_read_b128 v[34:37], v21 offset:16432
	s_waitcnt lgkmcnt(3)
	s_waitcnt vmcnt(23)
	v_fmac_f32_e32 v16, v104, v0
	v_fmac_f32_e32 v17, v104, v4
	v_fmac_f32_e32 v20, v104, v22
	s_waitcnt vmcnt(22)
	v_fmac_f32_e32 v16, v105, v1
	v_fmac_f32_e32 v17, v105, v5
	v_fmac_f32_e32 v20, v105, v23
	s_waitcnt vmcnt(21)
	v_fmac_f32_e32 v16, v106, v2
	v_fmac_f32_e32 v17, v106, v6
	v_fmac_f32_e32 v20, v106, v24
	s_waitcnt vmcnt(20)
	v_fmac_f32_e32 v16, v107, v3
	v_fmac_f32_e32 v17, v107, v7
	v_fmac_f32_e32 v20, v107, v25
	ds_read_b128 v[0:3], v21 offset:64
	ds_read_b128 v[4:7], v21 offset:8256
	ds_read_b128 v[22:25], v21 offset:16448
	s_waitcnt lgkmcnt(3)
	s_waitcnt vmcnt(19)
	v_fmac_f32_e32 v16, v108, v26
	v_fmac_f32_e32 v17, v108, v30
	v_fmac_f32_e32 v20, v108, v34
	s_waitcnt vmcnt(18)
	v_fmac_f32_e32 v16, v109, v27
	v_fmac_f32_e32 v17, v109, v31
	v_fmac_f32_e32 v20, v109, v35
	s_waitcnt vmcnt(17)
	v_fmac_f32_e32 v16, v110, v28
	v_fmac_f32_e32 v17, v110, v32
	v_fmac_f32_e32 v20, v110, v36
	s_waitcnt vmcnt(16)
	v_fmac_f32_e32 v16, v111, v29
	v_fmac_f32_e32 v17, v111, v33
	v_fmac_f32_e32 v20, v111, v37
	ds_read_b128 v[26:29], v21 offset:80
	ds_read_b128 v[30:33], v21 offset:8272
	ds_read_b128 v[34:37], v21 offset:16464
	s_waitcnt lgkmcnt(3)
	s_waitcnt vmcnt(15)
	v_fmac_f32_e32 v16, v112, v0
	v_fmac_f32_e32 v17, v112, v4
	v_fmac_f32_e32 v20, v112, v22
	s_waitcnt vmcnt(14)
	v_fmac_f32_e32 v16, v113, v1
	v_fmac_f32_e32 v17, v113, v5
	v_fmac_f32_e32 v20, v113, v23
	s_waitcnt vmcnt(13)
	v_fmac_f32_e32 v16, v114, v2
	v_fmac_f32_e32 v17, v114, v6
	v_fmac_f32_e32 v20, v114, v24
	s_waitcnt vmcnt(12)
	v_fmac_f32_e32 v16, v115, v3
	v_fmac_f32_e32 v17, v115, v7
	v_fmac_f32_e32 v20, v115, v25
	ds_read_b128 v[0:3], v21 offset:96
	ds_read_b128 v[4:7], v21 offset:8288
	ds_read_b128 v[22:25], v21 offset:16480
	s_waitcnt lgkmcnt(3)
	s_waitcnt vmcnt(11)
	v_fmac_f32_e32 v16, v116, v26
	v_fmac_f32_e32 v17, v116, v30
	v_fmac_f32_e32 v20, v116, v34
	s_waitcnt vmcnt(10)
	v_fmac_f32_e32 v16, v117, v27
	v_fmac_f32_e32 v17, v117, v31
	v_fmac_f32_e32 v20, v117, v35
	s_waitcnt vmcnt(9)
	v_fmac_f32_e32 v16, v118, v28
	v_fmac_f32_e32 v17, v118, v32
	v_fmac_f32_e32 v20, v118, v36
	s_waitcnt vmcnt(8)
	v_fmac_f32_e32 v16, v119, v29
	v_fmac_f32_e32 v17, v119, v33
	v_fmac_f32_e32 v20, v119, v37
	ds_read_b128 v[26:29], v21 offset:112
	ds_read_b128 v[30:33], v21 offset:8304
	ds_read_b128 v[34:37], v21 offset:16496
	s_waitcnt lgkmcnt(3)
	s_waitcnt vmcnt(7)
	v_fmac_f32_e32 v16, v120, v0
	v_fmac_f32_e32 v17, v120, v4
	v_fmac_f32_e32 v20, v120, v22
	s_waitcnt vmcnt(6)
	v_fmac_f32_e32 v16, v121, v1
	v_fmac_f32_e32 v17, v121, v5
	v_fmac_f32_e32 v20, v121, v23
	s_waitcnt vmcnt(5)
	v_fmac_f32_e32 v16, v122, v2
	v_fmac_f32_e32 v17, v122, v6
	v_fmac_f32_e32 v20, v122, v24
	s_waitcnt vmcnt(4)
	v_fmac_f32_e32 v16, v123, v3
	v_fmac_f32_e32 v17, v123, v7
	v_fmac_f32_e32 v20, v123, v25
	s_waitcnt lgkmcnt(0)
	s_waitcnt vmcnt(3)
	v_fmac_f32_e32 v16, v124, v26
	v_fmac_f32_e32 v17, v124, v30
	v_fmac_f32_e32 v20, v124, v34
	s_waitcnt vmcnt(2)
	v_fmac_f32_e32 v16, v125, v27
	v_fmac_f32_e32 v17, v125, v31
	v_fmac_f32_e32 v20, v125, v35
	s_waitcnt vmcnt(1)
	v_fmac_f32_e32 v16, v126, v28
	v_fmac_f32_e32 v17, v126, v32
	v_fmac_f32_e32 v20, v126, v36
	s_waitcnt vmcnt(0)
	v_fmac_f32_e32 v16, v127, v29
	v_fmac_f32_e32 v17, v127, v33
	v_fmac_f32_e32 v20, v127, v37
	v_add_u32_e32 v21, 0x80, v21
	s_cmp_eq_u32 s38, 0xc00000
	s_cbranch_scc0 .LBB0_246
	s_movk_i32 s16, 0x300
	v_mul_lo_u32 v0, v9, s16
	s_movk_i32 s16, 0xc0
	v_lshl_or_b32 v0, v19, 2, v0
	v_cmp_gt_i32_e32 vcc, s16, v8
	ds_write2st64_b32 v0, v16, v17 offset0:96 offset1:97
	ds_write_b32 v0, v20 offset:25088
	s_waitcnt lgkmcnt(0)
	s_barrier
	s_and_saveexec_b64 s[16:17], vcc
	s_xor_b64 s[38:39], exec, s[16:17]
	s_cbranch_execz .LBB0_235
	s_mov_b32 s16, 0x3fffffc0
	v_and_or_b32 v0, v8, s16, v19
	v_lshlrev_b32_e32 v3, 2, v0
	ds_read_b32 v2, v18 offset:24576
	ds_read2st64_b32 v[0:1], v3 offset0:99 offset1:102
	s_movk_i32 s16, 0x1800
	s_waitcnt lgkmcnt(0)
	v_add_f32_e32 v0, v2, v0
	v_add_f32_e32 v0, v0, v1
	ds_read_b32 v1, v3 offset:26880
	s_waitcnt lgkmcnt(0)
	v_add_f32_e32 v2, v0, v1
	v_lshl_add_u64 v[0:1], v[10:11], 2, s[6:7]
	v_add_co_u32_e32 v0, vcc, 0x6000, v0
	s_nop 1
	v_addc_co_u32_e32 v1, vcc, 0, v1, vcc
	global_load_dword v0, v[0:1], off
	s_waitcnt vmcnt(0)
	v_add_f32_e32 v2, v2, v0
	v_mul_lo_u32 v0, v9, s16
	s_movk_i32 s16, 0x4800
	v_add3_u32 v0, v0, v10, s16
	v_ashrrev_i32_e32 v1, 31, v0
	v_lshl_add_u64 v[0:1], v[0:1], 2, s[2:3]
	global_store_dword v[0:1], v2, off
	s_branch .LBB0_235
